# final rmsnorm phase: second bf16 row-half load hoisted with the first loads, second vmcnt(0) removed
# baseline (speedup 1.0000x reference)
; __device__ __forceinline__ float bflo(unsigned u) { return __uint_as_float(u << 16); }
; __device__ __forceinline__ float bfhi(unsigned u) { return __uint_as_float(u & 0xffff0000u); }
; __device__ __forceinline__ float row_scale(const float* part, int row) {
;     const f32x4* p = (const f32x4*)(part + (size_t)row * 16);
;     const f32x4 a = p[0], b = p[1], c = p[2], d = p[3];
;     const float s = ((a[0] + a[1]) + (a[2] + a[3])) + ((b[0] + b[1]) + (b[2] + b[3])) + ((c[0] + c[1]) + (c[2] + c[3])) + ((d[0] + d[1]) + (d[2] + d[3]));
;     return __builtin_amdgcn_rsqf(s * (1.0f / 1024.0f) + 1e-6f);
; }
; __global__ void __launch_bounds__(512, 2) mk_fwd(Args args) {
;     ...
;         for (int m = gw; m < T; m += NGW) {
;             const float rs = row_scale(PART, m);
;             const u32x4* xr = (const u32x4*)(XN + (size_t)m * DM); f32x4* yr = (f32x4*)(out + (size_t)m * DM);
; #pragma unroll
;             for (int j = 0; j < 2; ++j) { const u32x4 v = xr[lane + 64 * j];
;                 yr[2 * (lane + 64 * j)] = (f32x4){bflo(v.x), bfhi(v.x), bflo(v.y), bfhi(v.y)} * rs * w[2 * j];
;                 yr[2 * (lane + 64 * j) + 1] = (f32x4){bflo(v.z), bfhi(v.z), bflo(v.w), bfhi(v.w)} * rs * w[2 * j + 1]; }
;         }
.LBB0_1226:
	v_lshl_add_u64 v[32:33], s[34:35], 0, v[20:21]
	v_lshl_add_u64 v[24:25], s[34:35], 0, v[18:19]
	v_lshl_add_u64 v[44:45], v[32:33], 0, s[12:13]
	v_add_co_u32_e64 v48, s[0:1], s3, v24
	v_add_co_u32_e32 v46, vcc, 0x4000000, v32
	s_nop 0
	v_addc_co_u32_e64 v49, s[0:1], 0, v25, s[0:1]
	global_load_dwordx4 v[24:27], v[44:45], off offset:32
	global_load_dwordx4 v[28:31], v[44:45], off offset:16
	v_addc_co_u32_e32 v47, vcc, 0, v33, vcc
	global_load_dwordx4 v[32:35], v[46:47], off
	global_load_dwordx4 v[36:39], v[44:45], off offset:48
	global_load_dwordx4 v[40:43], v[48:49], off
	global_load_dwordx4 v[52:55], v[48:49], off offset:1024
	v_add_u32_e32 v16, s2, v16
	v_cmp_lt_i32_e32 vcc, s14, v16
	v_lshl_add_u64 v[18:19], v[18:19], 0, s[4:5]
	v_lshl_add_u64 v[20:21], v[20:21], 0, s[6:7]
	s_or_b64 s[10:11], vcc, s[10:11]
	s_waitcnt vmcnt(0)
	v_add_f32_e32 v24, v24, v25
	v_mov_b32_e32 v44, v29
	v_mov_b32_e32 v45, v30
	v_mov_b32_e32 v29, v31
	v_mov_b32_e32 v50, v33
	v_mov_b32_e32 v51, v34
	v_mov_b32_e32 v33, v35
	v_add_f32_e32 v26, v26, v27
	v_pk_add_f32 v[28:29], v[44:45], v[28:29]
	v_mov_b32_e32 v25, v38
	v_mov_b32_e32 v27, v39
	v_pk_add_f32 v[32:33], v[50:51], v[32:33]
	v_pk_add_f32 v[28:29], v[28:29], v[28:29] op_sel:[0,1] op_sel_hi:[1,0]
	v_pk_add_f32 v[24:25], v[24:25], v[26:27]
	v_pk_add_f32 v[26:27], v[32:33], v[32:33] op_sel:[0,1] op_sel_hi:[1,0]
	v_mov_b32_e32 v29, v37
	v_mov_b32_e32 v27, v36
	v_pk_add_f32 v[26:27], v[26:27], v[28:29]
	v_lshlrev_b32_e32 v30, 16, v40
	v_pk_add_f32 v[24:25], v[26:27], v[24:25]
	v_and_b32_e32 v31, 0xffff0000, v40
	v_add_f32_e32 v24, v24, v25
	v_fmamk_f32 v24, v24, 0x3a800000, v17
	v_rsq_f32_e32 v32, v24
	v_lshlrev_b32_e32 v40, 16, v41
	v_and_b32_e32 v41, 0xffff0000, v41
	v_lshlrev_b32_e32 v46, 16, v42
	v_and_b32_e32 v47, 0xffff0000, v42
	v_lshlrev_b32_e32 v42, 16, v43
	v_and_b32_e32 v43, 0xffff0000, v43
	v_pk_mul_f32 v[24:25], v[32:33], v[30:31] op_sel_hi:[0,1]
	v_pk_mul_f32 v[26:27], v[32:33], v[40:41] op_sel_hi:[0,1]
	v_pk_mul_f32 v[28:29], v[32:33], v[46:47] op_sel_hi:[0,1]
	v_pk_mul_f32 v[30:31], v[32:33], v[42:43] op_sel_hi:[0,1]
	v_pk_mul_f32 v[26:27], v[6:7], v[26:27]
	v_pk_mul_f32 v[24:25], v[4:5], v[24:25]
	v_pk_mul_f32 v[30:31], v[2:3], v[30:31]
	v_pk_mul_f32 v[28:29], v[0:1], v[28:29]
	global_store_dwordx4 v[22:23], v[24:27], off offset:-2064
	global_store_dwordx4 v[22:23], v[28:31], off offset:-2048
	s_nop 1
	v_lshlrev_b32_e32 v28, 16, v52
	v_and_b32_e32 v29, 0xffff0000, v52
	v_lshlrev_b32_e32 v24, 16, v53
	v_and_b32_e32 v25, 0xffff0000, v53
	v_lshlrev_b32_e32 v30, 16, v54
	v_and_b32_e32 v31, 0xffff0000, v54
	v_lshlrev_b32_e32 v26, 16, v55
	v_and_b32_e32 v27, 0xffff0000, v55
	v_pk_mul_f32 v[28:29], v[32:33], v[28:29] op_sel_hi:[0,1]
	v_pk_mul_f32 v[24:25], v[32:33], v[24:25] op_sel_hi:[0,1]
	v_pk_mul_f32 v[34:35], v[32:33], v[30:31] op_sel_hi:[0,1]
	v_pk_mul_f32 v[30:31], v[32:33], v[26:27] op_sel_hi:[0,1]
	v_pk_mul_f32 v[26:27], v[14:15], v[24:25]
	v_pk_mul_f32 v[24:25], v[12:13], v[28:29]
	v_pk_mul_f32 v[30:31], v[10:11], v[30:31]
	v_pk_mul_f32 v[28:29], v[8:9], v[34:35]
	global_store_dwordx4 v[22:23], v[24:27], off offset:-16
	global_store_dwordx4 v[22:23], v[28:31], off
	v_lshl_add_u64 v[22:23], v[22:23], 0, s[8:9]
	s_andn2_b64 exec, exec, s[10:11]
	s_cbranch_execnz .LBB0_1226
